# topk expert-id look-ups via v_perm_b32 byte tables: low bytes of the two 16-entry register arrays packed once per head, each look-up = 2 v_perm + 1 select (was a 16-step compare/select chain)
# speedup vs baseline: 1.0136x; 1.0016x over previous
.LBB0_1064:
	s_andn2_saveexec_b64 s[54:55], s[54:55]
	s_cbranch_execz .LBB0_1055
	s_lshl_b64 s[56:57], s[48:49], 2
	s_add_u32 s52, s52, s56
	s_addc_u32 s53, s53, s57
	s_mov_b32 s98, 0x0c0c0400
	s_mov_b32 s99, 0x04000c0c
	v_lshl_add_u64 v[16:17], v[16:17], 2, s[52:53]
	v_perm_b32 v33, v86, v85, s98
	v_perm_b32 v35, v88, v87, s99
	v_or_b32_e32 v85, v33, v35
	v_perm_b32 v36, v90, v89, s98
	v_perm_b32 v37, v92, v91, s99
	v_or_b32_e32 v89, v36, v37
	v_perm_b32 v33, v94, v93, s98
	v_perm_b32 v35, v96, v95, s99
	v_or_b32_e32 v93, v33, v35
	v_perm_b32 v36, v98, v97, s98
	v_perm_b32 v37, v100, v99, s99
	v_or_b32_e32 v97, v36, v37
	v_perm_b32 v33, v18, v12, s98
	v_perm_b32 v35, v20, v19, s99
	v_or_b32_e32 v18, v33, v35
	v_perm_b32 v36, v22, v21, s98
	v_perm_b32 v37, v24, v23, s99
	v_or_b32_e32 v22, v36, v37
	v_perm_b32 v33, v26, v25, s98
	v_perm_b32 v35, v28, v27, s99
	v_or_b32_e32 v26, v33, v35
	v_perm_b32 v36, v30, v29, s98
	v_perm_b32 v37, v3, v31, s99
	v_or_b32_e32 v30, v36, v37
	s_mov_b32 s98, 0x0c0c0c00
	v_not_b32_e32 v33, v34
	v_bfe_u32 v35, v33, 4, 4
	v_and_b32_e32 v36, 15, v33
	v_and_or_b32 v37, v35, 7, s98
	v_and_or_b32 v38, v36, 7, s98
	v_cmp_gt_u32_e32 vcc, 8, v35
	v_cmp_gt_u32_e64 s[100:101], 8, v36
	v_perm_b32 v86, v89, v85, v37
	v_perm_b32 v87, v97, v93, v37
	v_perm_b32 v88, v22, v18, v38
	v_perm_b32 v90, v30, v26, v38
	v_cndmask_b32_e32 v86, v87, v86, vcc
	v_cndmask_b32_e64 v88, v90, v88, s[100:101]
	v_and_b32_e32 v88, 0x7f, v88
	v_lshlrev_b32_e32 v86, 7, v86
	v_and_b32_e32 v86, 0x3f80, v86
	v_bitop3_b32 v3, v88, s82, v86 bitop3:0x36
	v_not_b32_e32 v33, v2
	v_bfe_u32 v35, v33, 4, 4
	v_and_b32_e32 v36, 15, v33
	v_and_or_b32 v37, v35, 7, s98
	v_and_or_b32 v38, v36, 7, s98
	v_cmp_gt_u32_e32 vcc, 8, v35
	v_cmp_gt_u32_e64 s[100:101], 8, v36
	v_perm_b32 v86, v89, v85, v37
	v_perm_b32 v87, v97, v93, v37
	v_perm_b32 v88, v22, v18, v38
	v_perm_b32 v90, v30, v26, v38
	v_cndmask_b32_e32 v86, v87, v86, vcc
	v_cndmask_b32_e64 v88, v90, v88, s[100:101]
	v_and_b32_e32 v88, 0x7f, v88
	v_lshlrev_b32_e32 v86, 7, v86
	v_and_b32_e32 v86, 0x3f80, v86
	v_bitop3_b32 v2, v88, s82, v86 bitop3:0x36
	v_not_b32_e32 v33, v1
	v_bfe_u32 v35, v33, 4, 4
	v_and_b32_e32 v36, 15, v33
	v_and_or_b32 v37, v35, 7, s98
	v_and_or_b32 v38, v36, 7, s98
	v_cmp_gt_u32_e32 vcc, 8, v35
	v_cmp_gt_u32_e64 s[100:101], 8, v36
	v_perm_b32 v86, v89, v85, v37
	v_perm_b32 v87, v97, v93, v37
	v_perm_b32 v88, v22, v18, v38
	v_perm_b32 v90, v30, v26, v38
	v_cndmask_b32_e32 v86, v87, v86, vcc
	v_cndmask_b32_e64 v88, v90, v88, s[100:101]
	v_and_b32_e32 v88, 0x7f, v88
	v_lshlrev_b32_e32 v86, 7, v86
	v_and_b32_e32 v86, 0x3f80, v86
	v_bitop3_b32 v1, v88, s82, v86 bitop3:0x36
	v_not_b32_e32 v33, v0
	v_bfe_u32 v35, v33, 4, 4
	v_and_b32_e32 v36, 15, v33
	v_and_or_b32 v37, v35, 7, s98
	v_and_or_b32 v38, v36, 7, s98
	v_cmp_gt_u32_e32 vcc, 8, v35
	v_cmp_gt_u32_e64 s[100:101], 8, v36
	v_perm_b32 v86, v89, v85, v37
	v_perm_b32 v87, v97, v93, v37
	v_perm_b32 v88, v22, v18, v38
	v_perm_b32 v90, v30, v26, v38
	v_cndmask_b32_e32 v86, v87, v86, vcc
	v_cndmask_b32_e64 v88, v90, v88, s[100:101]
	v_and_b32_e32 v88, 0x7f, v88
	v_lshlrev_b32_e32 v86, 7, v86
	v_and_b32_e32 v86, 0x3f80, v86
	v_bitop3_b32 v0, v88, s82, v86 bitop3:0x36
	v_not_b32_e32 v33, v7
	v_bfe_u32 v35, v33, 4, 4
	v_and_b32_e32 v36, 15, v33
	v_and_or_b32 v37, v35, 7, s98
	v_and_or_b32 v38, v36, 7, s98
	v_cmp_gt_u32_e32 vcc, 8, v35
	v_cmp_gt_u32_e64 s[100:101], 8, v36
	v_perm_b32 v86, v89, v85, v37
	v_perm_b32 v87, v97, v93, v37
	v_perm_b32 v88, v22, v18, v38
	v_perm_b32 v90, v30, v26, v38
	v_cndmask_b32_e32 v86, v87, v86, vcc
	v_cndmask_b32_e64 v88, v90, v88, s[100:101]
	v_and_b32_e32 v88, 0x7f, v88
	v_lshlrev_b32_e32 v86, 7, v86
	v_and_b32_e32 v86, 0x3f80, v86
	v_bitop3_b32 v7, v88, s82, v86 bitop3:0x36
	v_not_b32_e32 v33, v6
	v_bfe_u32 v35, v33, 4, 4
	v_and_b32_e32 v36, 15, v33
	v_and_or_b32 v37, v35, 7, s98
	v_and_or_b32 v38, v36, 7, s98
	v_cmp_gt_u32_e32 vcc, 8, v35
	v_cmp_gt_u32_e64 s[100:101], 8, v36
	v_perm_b32 v86, v89, v85, v37
	v_perm_b32 v87, v97, v93, v37
	v_perm_b32 v88, v22, v18, v38
	v_perm_b32 v90, v30, v26, v38
	v_cndmask_b32_e32 v86, v87, v86, vcc
	v_cndmask_b32_e64 v88, v90, v88, s[100:101]
	v_and_b32_e32 v88, 0x7f, v88
	v_lshlrev_b32_e32 v86, 7, v86
	v_and_b32_e32 v86, 0x3f80, v86
	v_bitop3_b32 v6, v88, s82, v86 bitop3:0x36
	v_not_b32_e32 v33, v5
	v_bfe_u32 v35, v33, 4, 4
	v_and_b32_e32 v36, 15, v33
	v_and_or_b32 v37, v35, 7, s98
	v_and_or_b32 v38, v36, 7, s98
	v_cmp_gt_u32_e32 vcc, 8, v35
	v_cmp_gt_u32_e64 s[100:101], 8, v36
	v_perm_b32 v86, v89, v85, v37
	v_perm_b32 v87, v97, v93, v37
	v_perm_b32 v88, v22, v18, v38
	v_perm_b32 v90, v30, v26, v38
	v_cndmask_b32_e32 v86, v87, v86, vcc
	v_cndmask_b32_e64 v88, v90, v88, s[100:101]
	v_and_b32_e32 v88, 0x7f, v88
	v_lshlrev_b32_e32 v86, 7, v86
	v_and_b32_e32 v86, 0x3f80, v86
	v_bitop3_b32 v5, v88, s82, v86 bitop3:0x36
	v_not_b32_e32 v33, v4
	v_bfe_u32 v35, v33, 4, 4
	v_and_b32_e32 v36, 15, v33
	v_and_or_b32 v37, v35, 7, s98
	v_and_or_b32 v38, v36, 7, s98
	v_cmp_gt_u32_e32 vcc, 8, v35
	v_cmp_gt_u32_e64 s[100:101], 8, v36
	v_perm_b32 v86, v89, v85, v37
	v_perm_b32 v87, v97, v93, v37
	v_perm_b32 v88, v22, v18, v38
	v_perm_b32 v90, v30, v26, v38
	v_cndmask_b32_e32 v86, v87, v86, vcc
	v_cndmask_b32_e64 v88, v90, v88, s[100:101]
	v_and_b32_e32 v88, 0x7f, v88
	v_lshlrev_b32_e32 v86, 7, v86
	v_and_b32_e32 v86, 0x3f80, v86
	v_bitop3_b32 v4, v88, s82, v86 bitop3:0x36
	v_not_b32_e32 v33, v11
	v_bfe_u32 v35, v33, 4, 4
	v_and_b32_e32 v36, 15, v33
	v_and_or_b32 v37, v35, 7, s98
	v_and_or_b32 v38, v36, 7, s98
	v_cmp_gt_u32_e32 vcc, 8, v35
	v_cmp_gt_u32_e64 s[100:101], 8, v36
	v_perm_b32 v86, v89, v85, v37
	v_perm_b32 v87, v97, v93, v37
	v_perm_b32 v88, v22, v18, v38
	v_perm_b32 v90, v30, v26, v38
	v_cndmask_b32_e32 v86, v87, v86, vcc
	v_cndmask_b32_e64 v88, v90, v88, s[100:101]
	v_and_b32_e32 v88, 0x7f, v88
	v_lshlrev_b32_e32 v86, 7, v86
	v_and_b32_e32 v86, 0x3f80, v86
	v_bitop3_b32 v11, v88, s82, v86 bitop3:0x36
	v_not_b32_e32 v33, v10
	v_bfe_u32 v35, v33, 4, 4
	v_and_b32_e32 v36, 15, v33
	v_and_or_b32 v37, v35, 7, s98
	v_and_or_b32 v38, v36, 7, s98
	v_cmp_gt_u32_e32 vcc, 8, v35
	v_cmp_gt_u32_e64 s[100:101], 8, v36
	v_perm_b32 v86, v89, v85, v37
	v_perm_b32 v87, v97, v93, v37
	v_perm_b32 v88, v22, v18, v38
	v_perm_b32 v90, v30, v26, v38
	v_cndmask_b32_e32 v86, v87, v86, vcc
	v_cndmask_b32_e64 v88, v90, v88, s[100:101]
	v_and_b32_e32 v88, 0x7f, v88
	v_lshlrev_b32_e32 v86, 7, v86
	v_and_b32_e32 v86, 0x3f80, v86
	v_bitop3_b32 v10, v88, s82, v86 bitop3:0x36
	v_not_b32_e32 v33, v9
	v_bfe_u32 v35, v33, 4, 4
	v_and_b32_e32 v36, 15, v33
	v_and_or_b32 v37, v35, 7, s98
	v_and_or_b32 v38, v36, 7, s98
	v_cmp_gt_u32_e32 vcc, 8, v35
	v_cmp_gt_u32_e64 s[100:101], 8, v36
	v_perm_b32 v86, v89, v85, v37
	v_perm_b32 v87, v97, v93, v37
	v_perm_b32 v88, v22, v18, v38
	v_perm_b32 v90, v30, v26, v38
	v_cndmask_b32_e32 v86, v87, v86, vcc
	v_cndmask_b32_e64 v88, v90, v88, s[100:101]
	v_and_b32_e32 v88, 0x7f, v88
	v_lshlrev_b32_e32 v86, 7, v86
	v_and_b32_e32 v86, 0x3f80, v86
	v_bitop3_b32 v9, v88, s82, v86 bitop3:0x36
	v_not_b32_e32 v33, v8
	v_bfe_u32 v35, v33, 4, 4
	v_and_b32_e32 v36, 15, v33
	v_and_or_b32 v37, v35, 7, s98
	v_and_or_b32 v38, v36, 7, s98
	v_cmp_gt_u32_e32 vcc, 8, v35
	v_cmp_gt_u32_e64 s[100:101], 8, v36
	v_perm_b32 v86, v89, v85, v37
	v_perm_b32 v87, v97, v93, v37
	v_perm_b32 v88, v22, v18, v38
	v_perm_b32 v90, v30, v26, v38
	v_cndmask_b32_e32 v86, v87, v86, vcc
	v_cndmask_b32_e64 v88, v90, v88, s[100:101]
	v_and_b32_e32 v88, 0x7f, v88
	v_lshlrev_b32_e32 v86, 7, v86
	v_and_b32_e32 v86, 0x3f80, v86
	v_bitop3_b32 v8, v88, s82, v86 bitop3:0x36
	v_not_b32_e32 v33, v15
	v_bfe_u32 v35, v33, 4, 4
	v_and_b32_e32 v36, 15, v33
	v_and_or_b32 v37, v35, 7, s98
	v_and_or_b32 v38, v36, 7, s98
	v_cmp_gt_u32_e32 vcc, 8, v35
	v_cmp_gt_u32_e64 s[100:101], 8, v36
	v_perm_b32 v86, v89, v85, v37
	v_perm_b32 v87, v97, v93, v37
	v_perm_b32 v88, v22, v18, v38
	v_perm_b32 v90, v30, v26, v38
	v_cndmask_b32_e32 v86, v87, v86, vcc
	v_cndmask_b32_e64 v88, v90, v88, s[100:101]
	v_and_b32_e32 v88, 0x7f, v88
	v_lshlrev_b32_e32 v86, 7, v86
	v_and_b32_e32 v86, 0x3f80, v86
	v_bitop3_b32 v15, v88, s82, v86 bitop3:0x36
	v_not_b32_e32 v33, v14
	v_bfe_u32 v35, v33, 4, 4
	v_and_b32_e32 v36, 15, v33
	v_and_or_b32 v37, v35, 7, s98
	v_and_or_b32 v38, v36, 7, s98
	v_cmp_gt_u32_e32 vcc, 8, v35
	v_cmp_gt_u32_e64 s[100:101], 8, v36
	v_perm_b32 v86, v89, v85, v37
	v_perm_b32 v87, v97, v93, v37
	v_perm_b32 v88, v22, v18, v38
	v_perm_b32 v90, v30, v26, v38
	v_cndmask_b32_e32 v86, v87, v86, vcc
	v_cndmask_b32_e64 v88, v90, v88, s[100:101]
	v_and_b32_e32 v88, 0x7f, v88
	v_lshlrev_b32_e32 v86, 7, v86
	v_and_b32_e32 v86, 0x3f80, v86
	v_bitop3_b32 v14, v88, s82, v86 bitop3:0x36
	v_not_b32_e32 v33, v13
	v_bfe_u32 v35, v33, 4, 4
	v_and_b32_e32 v36, 15, v33
	v_and_or_b32 v37, v35, 7, s98
	v_and_or_b32 v38, v36, 7, s98
	v_cmp_gt_u32_e32 vcc, 8, v35
	v_cmp_gt_u32_e64 s[100:101], 8, v36
	v_perm_b32 v86, v89, v85, v37
	v_perm_b32 v87, v97, v93, v37
	v_perm_b32 v88, v22, v18, v38
	v_perm_b32 v90, v30, v26, v38
	v_cndmask_b32_e32 v86, v87, v86, vcc
	v_cndmask_b32_e64 v88, v90, v88, s[100:101]
	v_and_b32_e32 v88, 0x7f, v88
	v_lshlrev_b32_e32 v86, 7, v86
	v_and_b32_e32 v86, 0x3f80, v86
	v_bitop3_b32 v13, v88, s82, v86 bitop3:0x36
	v_not_b32_e32 v33, v32
	v_bfe_u32 v35, v33, 4, 4
	v_and_b32_e32 v36, 15, v33
	v_and_or_b32 v37, v35, 7, s98
	v_and_or_b32 v38, v36, 7, s98
	v_cmp_gt_u32_e32 vcc, 8, v35
	v_cmp_gt_u32_e64 s[100:101], 8, v36
	v_perm_b32 v86, v89, v85, v37
	v_perm_b32 v87, v97, v93, v37
	v_perm_b32 v88, v22, v18, v38
	v_perm_b32 v90, v30, v26, v38
	v_cndmask_b32_e32 v86, v87, v86, vcc
	v_cndmask_b32_e64 v88, v90, v88, s[100:101]
	v_and_b32_e32 v88, 0x7f, v88
	v_lshlrev_b32_e32 v86, 7, v86
	v_and_b32_e32 v86, 0x3f80, v86
	v_bitop3_b32 v12, v88, s82, v86 bitop3:0x36
	v_lshl_add_u64 v[18:19], v[16:17], 0, s[42:43]
	v_add_co_u32_e32 v16, vcc, 0x34000000, v16
	s_nop 1
	v_addc_co_u32_e32 v17, vcc, 0, v17, vcc
	global_store_dwordx4 v[16:17], v[12:15], off
	global_store_dwordx4 v[18:19], v[8:11], off offset:16
	global_store_dwordx4 v[18:19], v[4:7], off offset:32
	global_store_dwordx4 v[18:19], v[0:3], off offset:48
	s_branch .LBB0_1055
